# GLA main loop: LDS fragment reads hoisted far ahead of MFMAs, state-update MFMAs moved before barrier, Q fragments kept in registers
# baseline (speedup 1.0000x reference)
.LBB0_352:
	ds_read_b128 v[248:251], v133
	v_add_u32_e32 v173, v134, v136
	ds_read_b128 v[196:199], v173
	v_add_u32_e32 v176, v137, v135
	ds_read_b128 v[212:215], v176 offset:16384
	v_add_u32_e32 v231, v137, v138
	ds_read_b128 v[216:219], v231 offset:16384
	v_add_u32_e32 v173, v134, v139
	ds_read_b128 v[200:203], v173
	v_add_u32_e32 v176, v140, v135
	ds_read_b128 v[220:223], v176 offset:16384
	v_add_u32_e32 v231, v140, v138
	ds_read_b128 v[224:227], v231 offset:16384
	v_add_u32_e32 v173, v134, v141
	ds_read_b128 v[204:207], v173
	v_add_u32_e32 v176, v142, v135
	ds_read_b128 v[232:235], v176 offset:16384
	v_add_u32_e32 v231, v142, v138
	ds_read_b128 v[236:239], v231 offset:16384
	v_add_u32_e32 v173, v134, v143
	ds_read_b128 v[208:211], v173
	v_add_u32_e32 v176, v144, v135
	ds_read_b128 v[240:243], v176 offset:16384
	v_add_u32_e32 v231, v144, v138
	ds_read_b128 v[244:247], v231 offset:16384
	s_waitcnt lgkmcnt(12)
	v_pk_mul_f32 v[64:65], v[112:113], v[248:249]
	v_pk_mul_f32 v[66:67], v[114:115], v[250:251]
	v_pk_mul_f32 v[68:69], v[108:109], v[248:249]
	v_pk_mul_f32 v[70:71], v[110:111], v[250:251]
	v_cvt_pk_bf16_f32 v72, v64, v65
	v_cvt_pk_bf16_f32 v73, v66, v67
	v_cvt_pk_bf16_f32 v74, v68, v69
	v_cvt_pk_bf16_f32 v75, v70, v71
	ds_write2st64_b64 v153, v[72:73], v[74:75] offset1:8
	v_pk_mul_f32 v[64:65], v[104:105], v[248:249]
	v_pk_mul_f32 v[66:67], v[106:107], v[250:251]
	v_pk_mul_f32 v[68:69], v[100:101], v[248:249]
	v_pk_mul_f32 v[70:71], v[102:103], v[250:251]
	v_cvt_pk_bf16_f32 v72, v64, v65
	v_cvt_pk_bf16_f32 v73, v66, v67
	v_cvt_pk_bf16_f32 v74, v68, v69
	v_cvt_pk_bf16_f32 v75, v70, v71
	ds_write2st64_b64 v153, v[72:73], v[74:75] offset0:16 offset1:24
	s_waitcnt lgkmcnt(12)
	v_mfma_f32_16x16x32_bf16 v[60:63], v[212:215], v[196:199], 0
	s_waitcnt lgkmcnt(11)
	v_mfma_f32_16x16x32_bf16 v[56:59], v[216:219], v[196:199], 0
	ds_read_b128 v[252:255], v162 offset:32768
	ds_read_b128 v[212:215], v163 offset:49152
	ds_read_b128 v[216:219], v164 offset:49152
	s_waitcnt lgkmcnt(12)
	v_mfma_f32_16x16x32_bf16 v[60:63], v[220:223], v[200:203], v[60:63]
	s_waitcnt lgkmcnt(11)
	v_mfma_f32_16x16x32_bf16 v[56:59], v[224:227], v[200:203], v[56:59]
	ds_read_b128 v[220:223], v165 offset:49152
	ds_read_b128 v[224:227], v166 offset:49152
	s_waitcnt lgkmcnt(11)
	v_mfma_f32_16x16x32_bf16 v[60:63], v[232:235], v[204:207], v[60:63]
	s_waitcnt lgkmcnt(10)
	v_mfma_f32_16x16x32_bf16 v[56:59], v[236:239], v[204:207], v[56:59]
	ds_read_b128 v[248:251], v167 offset:32768
	ds_read_b128 v[232:235], v168 offset:49152
	ds_read_b128 v[236:239], v169 offset:49152
	s_waitcnt lgkmcnt(11)
	v_mfma_f32_16x16x32_bf16 v[60:63], v[240:243], v[208:211], v[60:63]
	s_waitcnt lgkmcnt(10)
	v_mfma_f32_16x16x32_bf16 v[56:59], v[244:247], v[208:211], v[56:59]
	ds_read_b128 v[240:243], v170 offset:49152
	ds_read_b128 v[244:247], v171 offset:49152
	s_waitcnt lgkmcnt(8)
	v_mfma_f32_16x16x32_bf16 v[76:79], v[252:255], v[212:215], 0
	s_waitcnt lgkmcnt(7)
	v_mfma_f32_16x16x32_bf16 v[72:75], v[252:255], v[216:219], 0
	s_waitcnt lgkmcnt(6)
	v_mfma_f32_16x16x32_bf16 v[68:71], v[252:255], v[220:223], 0
	s_waitcnt lgkmcnt(5)
	v_mfma_f32_16x16x32_bf16 v[64:67], v[252:255], v[224:227], 0
	ds_read_b128 v[212:215], v157 offset:49152
	ds_read_b128 v[216:219], v158 offset:49152
	ds_read_b128 v[220:223], v160 offset:49152
	ds_read_b128 v[224:227], v161 offset:49152
	s_waitcnt lgkmcnt(7)
	v_mfma_f32_16x16x32_bf16 v[76:79], v[248:251], v[232:235], v[76:79]
	s_waitcnt lgkmcnt(6)
	v_mfma_f32_16x16x32_bf16 v[72:75], v[248:251], v[236:239], v[72:75]
	s_waitcnt lgkmcnt(5)
	v_mfma_f32_16x16x32_bf16 v[68:71], v[248:251], v[240:243], v[68:71]
	s_waitcnt lgkmcnt(4)
	v_mfma_f32_16x16x32_bf16 v[64:67], v[248:251], v[244:247], v[64:67]
	v_cndmask_b32_e64 v60, v60, 0, s[6:7]
	v_cndmask_b32_e64 v61, 0, v61, s[8:9]
	v_cndmask_b32_e64 v62, v62, 0, s[10:11]
	v_cndmask_b32_e64 v63, v63, 0, s[12:13]
	v_cndmask_b32_e64 v56, v56, 0, s[14:15]
	v_cndmask_b32_e64 v57, 0, v57, s[16:17]
	v_cndmask_b32_e64 v58, v58, 0, s[18:19]
	v_cndmask_b32_e64 v59, v59, 0, s[20:21]
	v_cvt_pk_bf16_f32 v60, v60, v61
	v_cvt_pk_bf16_f32 v61, v62, v63
	v_cvt_pk_bf16_f32 v56, v56, v57
	v_cvt_pk_bf16_f32 v57, v58, v59
	ds_write_b64 v154, v[60:61] offset:57344
	ds_write_b64 v155, v[56:57] offset:57344
	s_waitcnt lgkmcnt(0)
	s_barrier
	ds_read_b128 v[252:255], v156 offset:57344
	ds_read_b128 v[248:251], v159 offset:57344
	v_add_u32_e32 v173, v146, v135
	ds_read_b128 v[232:235], v173
	v_add_u32_e32 v176, v146, v138
	ds_read_b128 v[236:239], v176
	v_add_u32_e32 v231, v147, v135
	ds_read_b128 v[240:243], v231
	v_add_u32_e32 v173, v147, v138
	ds_read_b128 v[244:247], v173
	v_add_u32_e32 v116, s71, v145
	v_ashrrev_i32_e32 v117, 31, v116
	v_lshlrev_b32_e32 v84, 1, v82
	v_mov_b32_e32 v97, v85
	v_mov_b32_e32 v99, v85
	v_lshlrev_b64 v[228:229], 11, v[116:117]
	v_lshl_add_u64 v[228:229], s[28:29], 0, v[228:229]
	s_waitcnt lgkmcnt(5)
	v_mfma_f32_16x16x32_bf16 v[178:181], v[212:215], v[252:255], 0
	v_mfma_f32_16x16x32_bf16 v[182:185], v[216:219], v[252:255], 0
	s_waitcnt lgkmcnt(4)
	v_mfma_f32_16x16x32_bf16 v[178:181], v[220:223], v[248:251], v[178:181]
	v_mfma_f32_16x16x32_bf16 v[182:185], v[224:227], v[248:251], v[182:185]
	v_add_u32_e32 v176, v148, v135
	ds_read_b128 v[212:215], v176
	v_add_u32_e32 v231, v148, v138
	ds_read_b128 v[216:219], v231
	v_add_u32_e32 v173, v149, v135
	ds_read_b128 v[220:223], v173
	v_add_u32_e32 v176, v149, v138
	ds_read_b128 v[224:227], v176
	ds_read_b128 v[60:63], v150
	ds_read_b128 v[56:59], v151
	s_waitcnt lgkmcnt(9)
	v_mfma_f32_16x16x32_bf16 v[178:181], v[232:235], v[196:199], v[178:181]
	s_waitcnt lgkmcnt(8)
	v_mfma_f32_16x16x32_bf16 v[182:185], v[236:239], v[196:199], v[182:185]
	s_waitcnt lgkmcnt(7)
	v_mfma_f32_16x16x32_bf16 v[178:181], v[240:243], v[200:203], v[178:181]
	s_waitcnt lgkmcnt(6)
	v_mfma_f32_16x16x32_bf16 v[182:185], v[244:247], v[200:203], v[182:185]
	s_waitcnt lgkmcnt(5)
	v_mfma_f32_16x16x32_bf16 v[178:181], v[212:215], v[204:207], v[178:181]
	s_waitcnt lgkmcnt(4)
	v_mfma_f32_16x16x32_bf16 v[182:185], v[216:219], v[204:207], v[182:185]
	s_waitcnt lgkmcnt(3)
	v_mfma_f32_16x16x32_bf16 v[178:181], v[220:223], v[208:211], v[178:181]
	s_waitcnt lgkmcnt(2)
	v_mfma_f32_16x16x32_bf16 v[182:185], v[224:227], v[208:211], v[182:185]
	v_lshl_add_u64 v[174:175], v[228:229], 0, v[84:85]
	v_lshl_add_u64 v[174:175], v[174:175], 0, v[96:97]
	v_lshl_add_u64 v[228:229], v[228:229], 0, v[98:99]
	v_lshl_add_u64 v[228:229], v[228:229], 0, v[96:97]
	s_nop 4
	v_cvt_pk_bf16_f32 v186, v178, v179
	v_cvt_pk_bf16_f32 v187, v180, v181
	s_nop 0
	v_cvt_pk_bf16_f32 v188, v182, v183
	v_cvt_pk_bf16_f32 v189, v184, v185
	global_store_dwordx2 v[174:175], v[186:187], off
	global_store_dwordx2 v[228:229], v[188:189], off
	s_waitcnt lgkmcnt(0)
	s_barrier
	s_waitcnt vmcnt(8)
	ds_write_b128 v120, v[0:3]
	s_waitcnt vmcnt(7)
	ds_write_b128 v120, v[4:7] offset:16384
	s_waitcnt vmcnt(6)
	ds_write_b128 v121, v[8:11] offset:32768
	s_waitcnt vmcnt(5)
	ds_write_b128 v120, v[12:15] offset:8192
	s_waitcnt vmcnt(4)
	ds_write_b128 v120, v[16:19] offset:24576
	s_waitcnt vmcnt(3)
	ds_write_b128 v121, v[20:23] offset:40960
	s_waitcnt vmcnt(2)
	ds_write_b16 v122, v24 offset:49152
	ds_write_b16_d16_hi v123, v24 offset:49280
	ds_write_b16 v124, v25 offset:49408
	ds_write_b16_d16_hi v125, v25 offset:49536
	ds_write_b16 v126, v26 offset:49664
	ds_write_b16_d16_hi v127, v26 offset:49792
	ds_write_b16 v130, v27 offset:49920
	ds_write_b16_d16_hi v131, v27 offset:50048
	s_and_saveexec_b64 s[56:57], s[4:5]
	ds_write_b32 v152, v83
	s_or_b64 exec, exec, s[56:57]
	s_cmp_gt_u32 s72, 28
	s_waitcnt lgkmcnt(0)
	s_barrier
	s_cbranch_scc1 .LBB0_358
	v_add_u32_e32 v0, 0xc0, v177
	v_mad_i64_i32 v[4:5], s[56:57], v0, s73, v[86:87]
	s_ashr_i32 s31, s30, 31
	s_lshl_b64 s[56:57], s[30:31], 14
	v_lshl_add_u64 v[8:9], v[88:89], 0, s[56:57]
	v_mov_b32_e32 v81, v85
	v_lshl_add_u64 v[16:17], v[8:9], 0, v[80:81]
	v_add_u32_e32 v8, 0xe0, v177
	v_add_co_u32_e32 v20, vcc, 0x2000, v16
	v_add_u32_e32 v24, 0xc0, v95
	v_mad_i64_i32 v[18:19], s[56:57], v8, s73, v[86:87]
	v_addc_co_u32_e32 v21, vcc, 0, v17, vcc
	v_mad_i64_i32 v[24:25], s[56:57], v24, s73, v[92:93]
	global_load_dwordx4 v[0:3], v[4:5], off
	s_nop 0
	global_load_dwordx4 v[4:7], v[4:5], off offset:1024
	s_nop 0
	global_load_dwordx4 v[8:11], v[16:17], off
	global_load_dwordx4 v[12:15], v[18:19], off
	s_nop 0
	global_load_dwordx4 v[16:19], v[18:19], off offset:1024
	s_nop 0
	global_load_dwordx4 v[20:23], v[20:21], off
	v_mov_b32_e32 v83, 0
	global_load_dwordx4 v[24:27], v[24:25], off offset:2048
	s_and_saveexec_b64 s[56:57], s[4:5]
	s_cbranch_execz .LBB0_357
	v_ashrrev_i32_e32 v95, 31, v94
	v_lshlrev_b64 v[194:195], 11, v[94:95]
	v_lshl_add_u64 v[194:195], v[90:91], 0, v[194:195]
	global_load_dword v83, v[194:195], off

.LBB0_358:
	ds_read_b128 v[248:251], v133
	v_add_u32_e32 v173, v134, v136
	ds_read_b128 v[196:199], v173
	v_add_u32_e32 v176, v137, v135
	ds_read_b128 v[212:215], v176 offset:16384
	v_add_u32_e32 v231, v137, v138
	ds_read_b128 v[216:219], v231 offset:16384
	v_add_u32_e32 v173, v134, v139
	ds_read_b128 v[200:203], v173
	v_add_u32_e32 v176, v140, v135
	ds_read_b128 v[220:223], v176 offset:16384
	v_add_u32_e32 v231, v140, v138
	ds_read_b128 v[224:227], v231 offset:16384
	v_add_u32_e32 v173, v134, v141
	ds_read_b128 v[204:207], v173
	v_add_u32_e32 v176, v142, v135
	ds_read_b128 v[232:235], v176 offset:16384
	v_add_u32_e32 v231, v142, v138
	ds_read_b128 v[236:239], v231 offset:16384
	v_add_u32_e32 v173, v134, v143
	ds_read_b128 v[208:211], v173
	v_add_u32_e32 v176, v144, v135
	ds_read_b128 v[240:243], v176 offset:16384
	v_add_u32_e32 v231, v144, v138
	ds_read_b128 v[244:247], v231 offset:16384
	v_pk_mul_f32 v[76:77], v[60:61], v[76:77]
	v_pk_mul_f32 v[78:79], v[62:63], v[78:79]
	v_pk_mul_f32 v[72:73], v[60:61], v[72:73]
	v_pk_mul_f32 v[74:75], v[62:63], v[74:75]
	v_pk_mul_f32 v[68:69], v[60:61], v[68:69]
	v_pk_mul_f32 v[70:71], v[62:63], v[70:71]
	v_pk_mul_f32 v[64:65], v[60:61], v[64:65]
	v_pk_mul_f32 v[66:67], v[62:63], v[66:67]
	v_pk_fma_f32 v[112:113], v[112:113], v[56:57], v[76:77]
	v_pk_fma_f32 v[114:115], v[114:115], v[58:59], v[78:79]
	v_pk_fma_f32 v[108:109], v[108:109], v[56:57], v[72:73]
	v_pk_fma_f32 v[110:111], v[110:111], v[58:59], v[74:75]
	v_pk_fma_f32 v[104:105], v[104:105], v[56:57], v[68:69]
	v_pk_fma_f32 v[106:107], v[106:107], v[58:59], v[70:71]
	v_pk_fma_f32 v[100:101], v[100:101], v[56:57], v[64:65]
	v_pk_fma_f32 v[102:103], v[102:103], v[58:59], v[66:67]
	s_waitcnt lgkmcnt(12)
	v_pk_mul_f32 v[64:65], v[112:113], v[248:249]
	v_pk_mul_f32 v[66:67], v[114:115], v[250:251]
	v_pk_mul_f32 v[68:69], v[108:109], v[248:249]
	v_pk_mul_f32 v[70:71], v[110:111], v[250:251]
	v_cvt_pk_bf16_f32 v72, v64, v65
	v_cvt_pk_bf16_f32 v73, v66, v67
	v_cvt_pk_bf16_f32 v74, v68, v69
	v_cvt_pk_bf16_f32 v75, v70, v71
	ds_write2st64_b64 v153, v[72:73], v[74:75] offset1:8
	v_pk_mul_f32 v[64:65], v[104:105], v[248:249]
	v_pk_mul_f32 v[66:67], v[106:107], v[250:251]
	v_pk_mul_f32 v[68:69], v[100:101], v[248:249]
	v_pk_mul_f32 v[70:71], v[102:103], v[250:251]
	v_cvt_pk_bf16_f32 v72, v64, v65
	v_cvt_pk_bf16_f32 v73, v66, v67
	v_cvt_pk_bf16_f32 v74, v68, v69
	v_cvt_pk_bf16_f32 v75, v70, v71
	ds_write2st64_b64 v153, v[72:73], v[74:75] offset0:16 offset1:24
	s_waitcnt lgkmcnt(12)
	v_mfma_f32_16x16x32_bf16 v[60:63], v[212:215], v[196:199], 0
	s_waitcnt lgkmcnt(11)
	v_mfma_f32_16x16x32_bf16 v[56:59], v[216:219], v[196:199], 0
	ds_read_b128 v[252:255], v162 offset:32768
	ds_read_b128 v[212:215], v163 offset:49152
	ds_read_b128 v[216:219], v164 offset:49152
	s_waitcnt lgkmcnt(12)
	v_mfma_f32_16x16x32_bf16 v[60:63], v[220:223], v[200:203], v[60:63]
	s_waitcnt lgkmcnt(11)
	v_mfma_f32_16x16x32_bf16 v[56:59], v[224:227], v[200:203], v[56:59]
	ds_read_b128 v[220:223], v165 offset:49152
	ds_read_b128 v[224:227], v166 offset:49152
	s_waitcnt lgkmcnt(11)
	v_mfma_f32_16x16x32_bf16 v[60:63], v[232:235], v[204:207], v[60:63]
	s_waitcnt lgkmcnt(10)
	v_mfma_f32_16x16x32_bf16 v[56:59], v[236:239], v[204:207], v[56:59]
	ds_read_b128 v[248:251], v167 offset:32768
	ds_read_b128 v[232:235], v168 offset:49152
	ds_read_b128 v[236:239], v169 offset:49152
	s_waitcnt lgkmcnt(11)
	v_mfma_f32_16x16x32_bf16 v[60:63], v[240:243], v[208:211], v[60:63]
	s_waitcnt lgkmcnt(10)
	v_mfma_f32_16x16x32_bf16 v[56:59], v[244:247], v[208:211], v[56:59]
	ds_read_b128 v[240:243], v170 offset:49152
	ds_read_b128 v[244:247], v171 offset:49152
	s_waitcnt lgkmcnt(8)
	v_mfma_f32_16x16x32_bf16 v[76:79], v[252:255], v[212:215], 0
	s_waitcnt lgkmcnt(7)
	v_mfma_f32_16x16x32_bf16 v[72:75], v[252:255], v[216:219], 0
	s_waitcnt lgkmcnt(6)
	v_mfma_f32_16x16x32_bf16 v[68:71], v[252:255], v[220:223], 0
	s_waitcnt lgkmcnt(5)
	v_mfma_f32_16x16x32_bf16 v[64:67], v[252:255], v[224:227], 0
	ds_read_b128 v[212:215], v157 offset:49152
	ds_read_b128 v[216:219], v158 offset:49152
	ds_read_b128 v[220:223], v160 offset:49152
	ds_read_b128 v[224:227], v161 offset:49152
	s_waitcnt lgkmcnt(7)
	v_mfma_f32_16x16x32_bf16 v[76:79], v[248:251], v[232:235], v[76:79]
	s_waitcnt lgkmcnt(6)
	v_mfma_f32_16x16x32_bf16 v[72:75], v[248:251], v[236:239], v[72:75]
	s_waitcnt lgkmcnt(5)
	v_mfma_f32_16x16x32_bf16 v[68:71], v[248:251], v[240:243], v[68:71]
	s_waitcnt lgkmcnt(4)
	v_mfma_f32_16x16x32_bf16 v[64:67], v[248:251], v[244:247], v[64:67]
	v_cndmask_b32_e64 v60, v60, 0, s[6:7]
	v_cndmask_b32_e64 v61, 0, v61, s[8:9]
	v_cndmask_b32_e64 v62, v62, 0, s[10:11]
	v_cndmask_b32_e64 v63, v63, 0, s[12:13]
	v_cndmask_b32_e64 v56, v56, 0, s[14:15]
	v_cndmask_b32_e64 v57, 0, v57, s[16:17]
	v_cndmask_b32_e64 v58, v58, 0, s[18:19]
	v_cndmask_b32_e64 v59, v59, 0, s[20:21]
	v_cvt_pk_bf16_f32 v60, v60, v61
	v_cvt_pk_bf16_f32 v61, v62, v63
	v_cvt_pk_bf16_f32 v56, v56, v57
	v_cvt_pk_bf16_f32 v57, v58, v59
	ds_write_b64 v154, v[60:61] offset:57344
	ds_write_b64 v155, v[56:57] offset:57344
	s_waitcnt lgkmcnt(0)
	s_barrier
	ds_read_b128 v[252:255], v156 offset:57344
	ds_read_b128 v[248:251], v159 offset:57344
	v_add_u32_e32 v173, v146, v135
	ds_read_b128 v[232:235], v173
	v_add_u32_e32 v176, v146, v138
	ds_read_b128 v[236:239], v176
	v_add_u32_e32 v231, v147, v135
	ds_read_b128 v[240:243], v231
	v_add_u32_e32 v173, v147, v138
	ds_read_b128 v[244:247], v173
	v_add_u32_e32 v228, 64, v116
	v_ashrrev_i32_e32 v229, 31, v228
	v_mov_b32_e32 v97, v85
	v_mov_b32_e32 v99, v85
	v_lshlrev_b64 v[228:229], 11, v[228:229]
	v_lshl_add_u64 v[228:229], s[28:29], 0, v[228:229]
	s_waitcnt lgkmcnt(5)
	v_mfma_f32_16x16x32_bf16 v[178:181], v[212:215], v[252:255], 0
	v_mfma_f32_16x16x32_bf16 v[182:185], v[216:219], v[252:255], 0
	s_waitcnt lgkmcnt(4)
	v_mfma_f32_16x16x32_bf16 v[178:181], v[220:223], v[248:251], v[178:181]
	v_mfma_f32_16x16x32_bf16 v[182:185], v[224:227], v[248:251], v[182:185]
	v_add_u32_e32 v176, v148, v135
	ds_read_b128 v[212:215], v176
	v_add_u32_e32 v231, v148, v138
	ds_read_b128 v[216:219], v231
	v_add_u32_e32 v173, v149, v135
	ds_read_b128 v[220:223], v173
	v_add_u32_e32 v176, v149, v138
	ds_read_b128 v[224:227], v176
	ds_read_b128 v[60:63], v150
	ds_read_b128 v[56:59], v151
	s_waitcnt lgkmcnt(9)
	v_mfma_f32_16x16x32_bf16 v[178:181], v[232:235], v[196:199], v[178:181]
	s_waitcnt lgkmcnt(8)
	v_mfma_f32_16x16x32_bf16 v[182:185], v[236:239], v[196:199], v[182:185]
	s_waitcnt lgkmcnt(7)
	v_mfma_f32_16x16x32_bf16 v[178:181], v[240:243], v[200:203], v[178:181]
	s_waitcnt lgkmcnt(6)
	v_mfma_f32_16x16x32_bf16 v[182:185], v[244:247], v[200:203], v[182:185]
	s_waitcnt lgkmcnt(5)
	v_mfma_f32_16x16x32_bf16 v[178:181], v[212:215], v[204:207], v[178:181]
	s_waitcnt lgkmcnt(4)
	v_mfma_f32_16x16x32_bf16 v[182:185], v[216:219], v[204:207], v[182:185]
	s_waitcnt lgkmcnt(3)
	v_mfma_f32_16x16x32_bf16 v[178:181], v[220:223], v[208:211], v[178:181]
	s_waitcnt lgkmcnt(2)
	v_mfma_f32_16x16x32_bf16 v[182:185], v[224:227], v[208:211], v[182:185]
	v_lshl_add_u64 v[174:175], v[228:229], 0, v[84:85]
	v_lshl_add_u64 v[174:175], v[174:175], 0, v[96:97]
	v_lshl_add_u64 v[228:229], v[228:229], 0, v[98:99]
	v_lshl_add_u64 v[228:229], v[228:229], 0, v[96:97]
	s_andn2_b64 vcc, exec, s[54:55]
	s_nop 4
	v_cvt_pk_bf16_f32 v186, v178, v179
	v_cvt_pk_bf16_f32 v187, v180, v181
	s_nop 0
	v_cvt_pk_bf16_f32 v188, v182, v183
	v_cvt_pk_bf16_f32 v189, v184, v185
	global_store_dwordx2 v[174:175], v[186:187], off
	global_store_dwordx2 v[228:229], v[188:189], off
	s_waitcnt lgkmcnt(0)
	s_barrier
	s_cbranch_vccnz .LBB0_347
	ds_write_b128 v120, v[28:31]
	ds_write_b128 v120, v[32:35] offset:16384
	ds_write_b128 v121, v[40:43] offset:32768
	ds_write_b128 v120, v[36:39] offset:8192
	ds_write_b128 v120, v[44:47] offset:24576
	ds_write_b128 v121, v[48:51] offset:40960
	ds_write_b16 v122, v52 offset:49152
	ds_write_b16_d16_hi v123, v52 offset:49280
	ds_write_b16 v124, v53 offset:49408
	ds_write_b16_d16_hi v125, v53 offset:49536
	ds_write_b16 v126, v54 offset:49664
	ds_write_b16_d16_hi v127, v54 offset:49792
	ds_write_b16 v130, v55 offset:49920
	ds_write_b16_d16_hi v131, v55 offset:50048
	s_and_saveexec_b64 s[54:55], s[4:5]
	s_cbranch_execz .LBB0_346
	ds_write_b32 v152, v172
	s_branch .LBB0_346

	.amdhsa_kernel _Z11mega_kernel6Params
		.amdhsa_group_segment_fixed_size 0
		.amdhsa_private_segment_fixed_size 0
		.amdhsa_kernarg_size 584
		.amdhsa_user_sgpr_count 2
		.amdhsa_user_sgpr_dispatch_ptr 0
		.amdhsa_user_sgpr_queue_ptr 0
		.amdhsa_user_sgpr_kernarg_segment_ptr 1
		.amdhsa_user_sgpr_dispatch_id 0
		.amdhsa_user_sgpr_kernarg_preload_length 0
		.amdhsa_user_sgpr_kernarg_preload_offset 0
		.amdhsa_user_sgpr_private_segment_size 0
		.amdhsa_uses_dynamic_stack 0
		.amdhsa_enable_private_segment 0
		.amdhsa_system_sgpr_workgroup_id_x 1
		.amdhsa_system_sgpr_workgroup_id_y 0
		.amdhsa_system_sgpr_workgroup_id_z 0
		.amdhsa_system_sgpr_workgroup_info 0
		.amdhsa_system_vgpr_workitem_id 2
		.amdhsa_next_free_vgpr 256
		.amdhsa_next_free_sgpr 94
		.amdhsa_accum_offset 256
		.amdhsa_reserve_vcc 1
		.amdhsa_float_round_mode_32 0
		.amdhsa_float_round_mode_16_64 0
		.amdhsa_float_denorm_mode_32 3
		.amdhsa_float_denorm_mode_16_64 3
		.amdhsa_dx10_clamp 1
		.amdhsa_ieee_mode 1
		.amdhsa_fp16_overflow 0
		.amdhsa_tg_split 0
		.amdhsa_exception_fp_ieee_invalid_op 0
		.amdhsa_exception_fp_denorm_src 0
		.amdhsa_exception_fp_ieee_div_zero 0
		.amdhsa_exception_fp_ieee_overflow 0
		.amdhsa_exception_fp_ieee_underflow 0
		.amdhsa_exception_fp_ieee_inexact 0
		.amdhsa_exception_int_div_zero 0
	.end_amdhsa_kernel

amdhsa.kernels:
  - .agpr_count:     0
    .args:
      - .offset:         0
        .size:           328
        .value_kind:     by_value
      - .offset:         328
        .size:           4
        .value_kind:     hidden_block_count_x
      - .offset:         332
        .size:           4
        .value_kind:     hidden_block_count_y
      - .offset:         336
        .size:           4
        .value_kind:     hidden_block_count_z
      - .offset:         340
        .size:           2
        .value_kind:     hidden_group_size_x
      - .offset:         342
        .size:           2
        .value_kind:     hidden_group_size_y
      - .offset:         344
        .size:           2
        .value_kind:     hidden_group_size_z
      - .offset:         346
        .size:           2
        .value_kind:     hidden_remainder_x
      - .offset:         348
        .size:           2
        .value_kind:     hidden_remainder_y
      - .offset:         350
        .size:           2
        .value_kind:     hidden_remainder_z
      - .offset:         368
        .size:           8
        .value_kind:     hidden_global_offset_x
      - .offset:         376
        .size:           8
        .value_kind:     hidden_global_offset_y
      - .offset:         384
        .size:           8
        .value_kind:     hidden_global_offset_z
      - .offset:         392
        .size:           2
        .value_kind:     hidden_grid_dims
      - .offset:         416
        .size:           8
        .value_kind:     hidden_multigrid_sync_arg
      - .offset:         448
        .size:           4
        .value_kind:     hidden_dynamic_lds_size
    .group_segment_fixed_size: 0
    .kernarg_segment_align: 8
    .kernarg_segment_size: 584
    .language:       OpenCL C
    .language_version:
      - 2
      - 0
    .max_flat_workgroup_size: 512
    .name:           _Z11mega_kernel6Params
    .private_segment_fixed_size: 0
    .sgpr_count:     100
    .sgpr_spill_count: 16
    .symbol:         _Z11mega_kernel6Params.kd
    .uniform_work_group_size: 1
    .uses_dynamic_stack: false
    .vgpr_count:     256
    .vgpr_spill_count: 0
    .wavefront_size: 64
